# EpiSwiglu+EpiZ row-norm: one ss quad per lane + permlane16/32 cross-lane sum (8 loads per wave-tile instead of 32), on top of EpiResid prefetch
# speedup vs baseline: 1.0027x; 1.0027x over previous
; __device__ __forceinline__ u32x4 pack8(const f32x4& a, const f32x4& b) { u32x4 w; w.x = pk2(a[0], a[1]); w.y = pk2(a[2], a[3]); w.z = pk2(b[0], b[1]); w.w = pk2(b[2], b[3]); return w; }
; #define EPI_LOOP_ROWS for (int am_ = 0; am_ < 8; ++am_)
; __device__ __forceinline__ float ss_rstd(const float* ssrow) { const f32x4 a = *(const f32x4*)ssrow, b = *(const f32x4*)(ssrow + 4), c = *(const f32x4*)(ssrow + 8), d = *(const f32x4*)(ssrow + 12);
;     const float s = ((a[0] + a[1]) + (a[2] + a[3])) + ((b[0] + b[1]) + (b[2] + b[3])) + ((c[0] + c[1]) + (c[2] + c[3])) + ((d[0] + d[1]) + (d[2] + d[3])); return rsqrtf(s * (1.f / D) + 1e-6f); }
;     __device__ __forceinline__ void operator()(const f32x4 (&acc)[2][2][4][2], const pg8::Unit& u, int wr, int wc, int fr, int fq) const { asm volatile("" : "+v"(fr), "+v"(fq));
; #pragma unroll
;         EPI_LOOP_ROWS { EPI_AM const int row = u.pm * 256 + ai * 128 + wr * 64 + m * 16 + fr; const float rstd = ss_rstd(ss + (size_t)row * 16);
; #pragma unroll
;             for (int bj = 0; bj < 2; ++bj) { const int col0 = u.pn * 256 + bj * 128 + wc * 32 + 8 * fq;
;                 *(u32x4*)(z + (size_t)row * NIN + col0) = pack8(acc[ai][bj][m][0] * rstd, acc[ai][bj][m][1] * rstd); } }
.LBB0_1247:
	v_mov_b32_e32 v139, v146
	v_mov_b32_e32 v142, v147
	s_lshl_b32 s33, s78, 8
	s_add_i32 s33, s33, s54
	v_add_u32_e32 v142, s33, v142
	v_ashrrev_i32_e32 v143, 31, v142
	s_lshl_b32 s33, s77, 8
	s_or_b32 s33, s33, s55
	v_lshl_add_u32 v144, v139, 3, s33
	v_ashrrev_i32_e32 v145, 31, v144
	v_lshlrev_b64 v[228:229], 6, v[142:143]
	v_lshl_add_u64 v[228:229], s[14:15], 0, v[228:229]
	v_and_b32_e32 v174, 0x30, v166
	v_mov_b32_e32 v175, 0
	v_lshl_add_u64 v[228:229], v[174:175], 0, v[228:229]
	v_add_co_u32_e32 v226, vcc, 0x2000, v228
	s_nop 1
	v_addc_co_u32_e32 v227, vcc, 0, v229, vcc
	global_load_dwordx4 v[176:179], v[228:229], off offset:0
	global_load_dwordx4 v[180:183], v[228:229], off offset:1024
	global_load_dwordx4 v[184:187], v[228:229], off offset:2048
	global_load_dwordx4 v[188:191], v[228:229], off offset:3072
	global_load_dwordx4 v[192:195], v[226:227], off offset:0
	global_load_dwordx4 v[196:199], v[226:227], off offset:1024
	global_load_dwordx4 v[200:203], v[226:227], off offset:2048
	global_load_dwordx4 v[204:207], v[226:227], off offset:3072
	s_waitcnt vmcnt(0)
	v_add_f32_e32 v176, v176, v177
	v_add_f32_e32 v180, v180, v181
	v_add_f32_e32 v184, v184, v185
	v_add_f32_e32 v188, v188, v189
	v_add_f32_e32 v192, v192, v193
	v_add_f32_e32 v196, v196, v197
	v_add_f32_e32 v200, v200, v201
	v_add_f32_e32 v204, v204, v205
	v_add_f32_e32 v178, v178, v179
	v_add_f32_e32 v182, v182, v183
	v_add_f32_e32 v186, v186, v187
	v_add_f32_e32 v190, v190, v191
	v_add_f32_e32 v194, v194, v195
	v_add_f32_e32 v198, v198, v199
	v_add_f32_e32 v202, v202, v203
	v_add_f32_e32 v206, v206, v207
	v_add_f32_e32 v176, v176, v178
	v_add_f32_e32 v180, v180, v182
	v_add_f32_e32 v184, v184, v186
	v_add_f32_e32 v188, v188, v190
	v_add_f32_e32 v192, v192, v194
	v_add_f32_e32 v196, v196, v198
	v_add_f32_e32 v200, v200, v202
	v_add_f32_e32 v204, v204, v206
	v_mov_b32_e32 v177, v176
	v_mov_b32_e32 v181, v180
	v_mov_b32_e32 v185, v184
	v_mov_b32_e32 v189, v188
	v_mov_b32_e32 v193, v192
	v_mov_b32_e32 v197, v196
	v_mov_b32_e32 v201, v200
	v_mov_b32_e32 v205, v204
	v_permlane16_swap_b32 v176, v177
	v_permlane16_swap_b32 v180, v181
	v_permlane16_swap_b32 v184, v185
	v_permlane16_swap_b32 v188, v189
	v_permlane16_swap_b32 v192, v193
	v_permlane16_swap_b32 v196, v197
	v_permlane16_swap_b32 v200, v201
	v_permlane16_swap_b32 v204, v205
	v_add_f32_e32 v176, v176, v177
	v_add_f32_e32 v180, v180, v181
	v_add_f32_e32 v184, v184, v185
	v_add_f32_e32 v188, v188, v189
	v_add_f32_e32 v192, v192, v193
	v_add_f32_e32 v196, v196, v197
	v_add_f32_e32 v200, v200, v201
	v_add_f32_e32 v204, v204, v205
	v_mov_b32_e32 v177, v176
	v_mov_b32_e32 v181, v180
	v_mov_b32_e32 v185, v184
	v_mov_b32_e32 v189, v188
	v_mov_b32_e32 v193, v192
	v_mov_b32_e32 v197, v196
	v_mov_b32_e32 v201, v200
	v_mov_b32_e32 v205, v204
	v_permlane32_swap_b32 v176, v177
	v_permlane32_swap_b32 v180, v181
	v_permlane32_swap_b32 v184, v185
	v_permlane32_swap_b32 v188, v189
	v_permlane32_swap_b32 v192, v193
	v_permlane32_swap_b32 v196, v197
	v_permlane32_swap_b32 v200, v201
	v_permlane32_swap_b32 v204, v205
	v_add_f32_e32 v176, v176, v177
	v_add_f32_e32 v180, v180, v181
	v_add_f32_e32 v184, v184, v185
	v_add_f32_e32 v188, v188, v189
	v_add_f32_e32 v192, v192, v193
	v_add_f32_e32 v196, v196, v197
	v_add_f32_e32 v200, v200, v201
	v_add_f32_e32 v204, v204, v205
	v_fmamk_f32 v176, v176, 0x3a800000, v138
	v_cmp_gt_f32_e32 vcc, s64, v176
	v_mul_f32_e32 v177, 0x4b800000, v176
	s_nop 0
	v_cndmask_b32_e32 v176, v176, v177, vcc
	v_rsq_f32_e32 v176, v176
	s_nop 0
	v_mul_f32_e32 v177, 0x45800000, v176
	v_cndmask_b32_e32 v246, v176, v177, vcc
	v_fmamk_f32 v180, v180, 0x3a800000, v138
	v_cmp_gt_f32_e32 vcc, s64, v180
	v_mul_f32_e32 v181, 0x4b800000, v180
	s_nop 0
	v_cndmask_b32_e32 v180, v180, v181, vcc
	v_rsq_f32_e32 v180, v180
	s_nop 0
	v_mul_f32_e32 v181, 0x45800000, v180
	v_cndmask_b32_e32 v247, v180, v181, vcc
	v_fmamk_f32 v184, v184, 0x3a800000, v138
	v_cmp_gt_f32_e32 vcc, s64, v184
	v_mul_f32_e32 v185, 0x4b800000, v184
	s_nop 0
	v_cndmask_b32_e32 v184, v184, v185, vcc
	v_rsq_f32_e32 v184, v184
	s_nop 0
	v_mul_f32_e32 v185, 0x45800000, v184
	v_cndmask_b32_e32 v248, v184, v185, vcc
	v_fmamk_f32 v188, v188, 0x3a800000, v138
	v_cmp_gt_f32_e32 vcc, s64, v188
	v_mul_f32_e32 v189, 0x4b800000, v188
	s_nop 0
	v_cndmask_b32_e32 v188, v188, v189, vcc
	v_rsq_f32_e32 v188, v188
	s_nop 0
	v_mul_f32_e32 v189, 0x45800000, v188
	v_cndmask_b32_e32 v249, v188, v189, vcc
	v_fmamk_f32 v192, v192, 0x3a800000, v138
	v_cmp_gt_f32_e32 vcc, s64, v192
	v_mul_f32_e32 v193, 0x4b800000, v192
	s_nop 0
	v_cndmask_b32_e32 v192, v192, v193, vcc
	v_rsq_f32_e32 v192, v192
	s_nop 0
	v_mul_f32_e32 v193, 0x45800000, v192
	v_cndmask_b32_e32 v250, v192, v193, vcc
	v_fmamk_f32 v196, v196, 0x3a800000, v138
	v_cmp_gt_f32_e32 vcc, s64, v196
	v_mul_f32_e32 v197, 0x4b800000, v196
	s_nop 0
	v_cndmask_b32_e32 v196, v196, v197, vcc
	v_rsq_f32_e32 v196, v196
	s_nop 0
	v_mul_f32_e32 v197, 0x45800000, v196
	v_cndmask_b32_e32 v251, v196, v197, vcc
	v_fmamk_f32 v200, v200, 0x3a800000, v138
	v_cmp_gt_f32_e32 vcc, s64, v200
	v_mul_f32_e32 v201, 0x4b800000, v200
	s_nop 0
	v_cndmask_b32_e32 v200, v200, v201, vcc
	v_rsq_f32_e32 v200, v200
	s_nop 0
	v_mul_f32_e32 v201, 0x45800000, v200
	v_cndmask_b32_e32 v252, v200, v201, vcc
	v_fmamk_f32 v204, v204, 0x3a800000, v138
	v_cmp_gt_f32_e32 vcc, s64, v204
	v_mul_f32_e32 v205, 0x4b800000, v204
	s_nop 0
	v_cndmask_b32_e32 v204, v204, v205, vcc
	v_rsq_f32_e32 v204, v204
	s_nop 0
	v_mul_f32_e32 v205, 0x45800000, v204
	v_cndmask_b32_e32 v253, v204, v205, vcc
	v_mov_b32_e32 v150, v246
	v_pk_mul_f32 v[120:121], v[120:121], v[150:151] op_sel_hi:[1,0]
; __device__ __forceinline__ u32x4 pack8(const f32x4& a, const f32x4& b) { u32x4 w; w.x = pk2(a[0], a[1]); w.y = pk2(a[2], a[3]); w.z = pk2(b[0], b[1]); w.w = pk2(b[2], b[3]); return w; }
; #define EPI_LOOP_ROWS for (int am_ = 0; am_ < 8; ++am_)
;     __device__ __forceinline__ void operator()(const f32x4 (&acc)[2][2][4][2], const pg8::Unit& u, int wr, int wc, int fr, int fq) const { asm volatile("" : "+v"(fr), "+v"(fq));
;     ...
;         EPI_LOOP_ROWS { EPI_AM const int row = u.pm * 256 + ai * 128 + wr * 64 + m * 16 + fr; const float rstd = ss_rstd(ss + (size_t)row * 16);
; #pragma unroll
;             for (int bj = 0; bj < 2; ++bj) { const int col0 = u.pn * 256 + bj * 128 + wc * 32 + 8 * fq;
;                 *(u32x4*)(z + (size_t)row * NIN + col0) = pack8(acc[ai][bj][m][0] * rstd, acc[ai][bj][m][1] * rstd); } }
	v_pk_mul_f32 v[122:123], v[122:123], v[150:151] op_sel_hi:[1,0]
	v_pk_mul_f32 v[152:153], v[126:127], v[150:151] op_sel_hi:[1,0]
	v_pk_mul_f32 v[126:127], v[124:125], v[150:151] op_sel_hi:[1,0]
	v_cvt_pk_bf16_f32 v124, v120, v121
	v_mov_b64_e32 v[120:121], s[90:91]
	v_cvt_pk_bf16_f32 v125, v122, v123
	v_cvt_pk_bf16_f32 v126, v126, v127
	v_cvt_pk_bf16_f32 v127, v152, v153
	v_mad_i64_i32 v[152:153], s[36:37], v142, s75, v[120:121]
	v_lshlrev_b64 v[122:123], 1, v[144:145]
	v_lshl_add_u64 v[144:145], v[152:153], 0, v[122:123]
	global_store_dwordx4 v[144:145], v[124:127], off
	v_pk_mul_f32 v[118:119], v[118:119], v[150:151] op_sel_hi:[1,0]
	v_pk_mul_f32 v[116:117], v[116:117], v[150:151] op_sel_hi:[1,0]
	v_pk_mul_f32 v[124:125], v[114:115], v[150:151] op_sel_hi:[1,0]
	v_pk_mul_f32 v[114:115], v[112:113], v[150:151] op_sel_hi:[1,0]
	v_cvt_pk_bf16_f32 v112, v116, v117
	v_cvt_pk_bf16_f32 v113, v118, v119
	v_cvt_pk_bf16_f32 v114, v114, v115
	v_cvt_pk_bf16_f32 v115, v124, v125
	global_store_dwordx4 v[144:145], v[112:115], off offset:256
	v_add_u32_e32 v144, 16, v142
	v_ashrrev_i32_e32 v145, 31, v144
	v_mov_b32_e32 v112, v247
	v_pk_mul_f32 v[108:109], v[108:109], v[112:113] op_sel_hi:[1,0]
	v_pk_mul_f32 v[110:111], v[110:111], v[112:113] op_sel_hi:[1,0]
	v_pk_mul_f32 v[114:115], v[106:107], v[112:113] op_sel_hi:[1,0]
	v_pk_mul_f32 v[106:107], v[104:105], v[112:113] op_sel_hi:[1,0]
	v_cvt_pk_bf16_f32 v104, v108, v109
	v_mad_i64_i32 v[108:109], s[36:37], v144, s75, v[120:121]
	v_cvt_pk_bf16_f32 v105, v110, v111
	v_cvt_pk_bf16_f32 v106, v106, v107
	v_cvt_pk_bf16_f32 v107, v114, v115
	v_lshl_add_u64 v[108:109], v[108:109], 0, v[122:123]
	global_store_dwordx4 v[108:109], v[104:107], off
	v_pk_mul_f32 v[102:103], v[102:103], v[112:113] op_sel_hi:[1,0]
	v_pk_mul_f32 v[100:101], v[100:101], v[112:113] op_sel_hi:[1,0]
	v_pk_mul_f32 v[104:105], v[98:99], v[112:113] op_sel_hi:[1,0]
	v_pk_mul_f32 v[98:99], v[96:97], v[112:113] op_sel_hi:[1,0]
	v_add_u32_e32 v112, 32, v142
	v_cvt_pk_bf16_f32 v96, v100, v101
	v_cvt_pk_bf16_f32 v97, v102, v103
	v_cvt_pk_bf16_f32 v98, v98, v99
	v_cvt_pk_bf16_f32 v99, v104, v105
	v_ashrrev_i32_e32 v113, 31, v112
	global_store_dwordx4 v[108:109], v[96:99], off offset:256
	s_nop 1
	v_mov_b32_e32 v96, v248
	v_pk_mul_f32 v[92:93], v[92:93], v[96:97] op_sel_hi:[1,0]
	v_pk_mul_f32 v[94:95], v[94:95], v[96:97] op_sel_hi:[1,0]
	v_pk_mul_f32 v[98:99], v[90:91], v[96:97] op_sel_hi:[1,0]
	v_pk_mul_f32 v[90:91], v[88:89], v[96:97] op_sel_hi:[1,0]
	v_cvt_pk_bf16_f32 v88, v92, v93
	v_mad_i64_i32 v[92:93], s[36:37], v112, s75, v[120:121]
	v_cvt_pk_bf16_f32 v89, v94, v95
	v_cvt_pk_bf16_f32 v90, v90, v91
	v_cvt_pk_bf16_f32 v91, v98, v99
	v_lshl_add_u64 v[92:93], v[92:93], 0, v[122:123]
	global_store_dwordx4 v[92:93], v[88:91], off
	v_pk_mul_f32 v[86:87], v[86:87], v[96:97] op_sel_hi:[1,0]
	v_pk_mul_f32 v[84:85], v[84:85], v[96:97] op_sel_hi:[1,0]
	v_pk_mul_f32 v[88:89], v[82:83], v[96:97] op_sel_hi:[1,0]
	v_pk_mul_f32 v[82:83], v[80:81], v[96:97] op_sel_hi:[1,0]
	v_add_u32_e32 v96, 48, v142
	v_cvt_pk_bf16_f32 v80, v84, v85
	v_cvt_pk_bf16_f32 v81, v86, v87
	v_cvt_pk_bf16_f32 v82, v82, v83
	v_cvt_pk_bf16_f32 v83, v88, v89
	v_ashrrev_i32_e32 v97, 31, v96
	global_store_dwordx4 v[92:93], v[80:83], off offset:256
	s_nop 1
	v_mov_b32_e32 v80, v249
	v_pk_mul_f32 v[76:77], v[76:77], v[80:81] op_sel_hi:[1,0]
	v_pk_mul_f32 v[78:79], v[78:79], v[80:81] op_sel_hi:[1,0]
	v_pk_mul_f32 v[82:83], v[74:75], v[80:81] op_sel_hi:[1,0]
	v_pk_mul_f32 v[74:75], v[72:73], v[80:81] op_sel_hi:[1,0]
	v_cvt_pk_bf16_f32 v72, v76, v77
	v_mad_i64_i32 v[76:77], s[36:37], v96, s75, v[120:121]
	v_cvt_pk_bf16_f32 v73, v78, v79
	v_cvt_pk_bf16_f32 v74, v74, v75
	v_cvt_pk_bf16_f32 v75, v82, v83
	v_lshl_add_u64 v[76:77], v[76:77], 0, v[122:123]
	global_store_dwordx4 v[76:77], v[72:75], off
	v_pk_mul_f32 v[70:71], v[70:71], v[80:81] op_sel_hi:[1,0]
	v_pk_mul_f32 v[68:69], v[68:69], v[80:81] op_sel_hi:[1,0]
	v_pk_mul_f32 v[72:73], v[66:67], v[80:81] op_sel_hi:[1,0]
	v_pk_mul_f32 v[66:67], v[64:65], v[80:81] op_sel_hi:[1,0]
	v_add_u32_e32 v80, 0x80, v142
	v_cvt_pk_bf16_f32 v64, v68, v69
	v_cvt_pk_bf16_f32 v65, v70, v71
	v_cvt_pk_bf16_f32 v66, v66, v67
	v_cvt_pk_bf16_f32 v67, v72, v73
	v_ashrrev_i32_e32 v81, 31, v80
	global_store_dwordx4 v[76:77], v[64:67], off offset:256
; __device__ __forceinline__ u32x4 pack8(const f32x4& a, const f32x4& b) { u32x4 w; w.x = pk2(a[0], a[1]); w.y = pk2(a[2], a[3]); w.z = pk2(b[0], b[1]); w.w = pk2(b[2], b[3]); return w; }
; #define EPI_LOOP_ROWS for (int am_ = 0; am_ < 8; ++am_)
;     __device__ __forceinline__ void operator()(const f32x4 (&acc)[2][2][4][2], const pg8::Unit& u, int wr, int wc, int fr, int fq) const { asm volatile("" : "+v"(fr), "+v"(fq));
;     ...
;         EPI_LOOP_ROWS { EPI_AM const int row = u.pm * 256 + ai * 128 + wr * 64 + m * 16 + fr; const float rstd = ss_rstd(ss + (size_t)row * 16);
; #pragma unroll
;             for (int bj = 0; bj < 2; ++bj) { const int col0 = u.pn * 256 + bj * 128 + wc * 32 + 8 * fq;
;                 *(u32x4*)(z + (size_t)row * NIN + col0) = pack8(acc[ai][bj][m][0] * rstd, acc[ai][bj][m][1] * rstd); } }
	s_nop 1
	v_mov_b32_e32 v64, v250
	v_pk_mul_f32 v[60:61], v[60:61], v[64:65] op_sel_hi:[1,0]
	v_pk_mul_f32 v[62:63], v[62:63], v[64:65] op_sel_hi:[1,0]
	v_pk_mul_f32 v[66:67], v[58:59], v[64:65] op_sel_hi:[1,0]
	v_pk_mul_f32 v[58:59], v[56:57], v[64:65] op_sel_hi:[1,0]
	v_cvt_pk_bf16_f32 v56, v60, v61
	v_mad_i64_i32 v[60:61], s[36:37], v80, s75, v[120:121]
	v_cvt_pk_bf16_f32 v57, v62, v63
	v_cvt_pk_bf16_f32 v58, v58, v59
	v_cvt_pk_bf16_f32 v59, v66, v67
	v_lshl_add_u64 v[60:61], v[60:61], 0, v[122:123]
	global_store_dwordx4 v[60:61], v[56:59], off
	v_pk_mul_f32 v[54:55], v[54:55], v[64:65] op_sel_hi:[1,0]
	v_pk_mul_f32 v[52:53], v[52:53], v[64:65] op_sel_hi:[1,0]
	v_pk_mul_f32 v[56:57], v[50:51], v[64:65] op_sel_hi:[1,0]
	v_pk_mul_f32 v[50:51], v[48:49], v[64:65] op_sel_hi:[1,0]
	v_add_u32_e32 v64, 0x90, v142
	v_cvt_pk_bf16_f32 v48, v52, v53
	v_cvt_pk_bf16_f32 v49, v54, v55
	v_cvt_pk_bf16_f32 v50, v50, v51
	v_cvt_pk_bf16_f32 v51, v56, v57
	v_ashrrev_i32_e32 v65, 31, v64
	global_store_dwordx4 v[60:61], v[48:51], off offset:256
	s_nop 1
	v_mov_b32_e32 v48, v251
	v_pk_mul_f32 v[44:45], v[44:45], v[48:49] op_sel_hi:[1,0]
	v_pk_mul_f32 v[46:47], v[46:47], v[48:49] op_sel_hi:[1,0]
	v_pk_mul_f32 v[50:51], v[42:43], v[48:49] op_sel_hi:[1,0]
	v_pk_mul_f32 v[42:43], v[40:41], v[48:49] op_sel_hi:[1,0]
	v_cvt_pk_bf16_f32 v40, v44, v45
	v_mad_i64_i32 v[44:45], s[36:37], v64, s75, v[120:121]
	v_cvt_pk_bf16_f32 v41, v46, v47
	v_cvt_pk_bf16_f32 v42, v42, v43
	v_cvt_pk_bf16_f32 v43, v50, v51
	v_lshl_add_u64 v[44:45], v[44:45], 0, v[122:123]
	global_store_dwordx4 v[44:45], v[40:43], off
	v_pk_mul_f32 v[38:39], v[38:39], v[48:49] op_sel_hi:[1,0]
	v_pk_mul_f32 v[36:37], v[36:37], v[48:49] op_sel_hi:[1,0]
	v_pk_mul_f32 v[40:41], v[34:35], v[48:49] op_sel_hi:[1,0]
	v_pk_mul_f32 v[34:35], v[32:33], v[48:49] op_sel_hi:[1,0]
	v_add_u32_e32 v48, 0xa0, v142
	v_cvt_pk_bf16_f32 v32, v36, v37
	v_cvt_pk_bf16_f32 v33, v38, v39
	v_cvt_pk_bf16_f32 v34, v34, v35
	v_cvt_pk_bf16_f32 v35, v40, v41
	v_ashrrev_i32_e32 v49, 31, v48
	global_store_dwordx4 v[44:45], v[32:35], off offset:256
	s_nop 1
	v_mov_b32_e32 v32, v252
	v_pk_mul_f32 v[28:29], v[28:29], v[32:33] op_sel_hi:[1,0]
	v_pk_mul_f32 v[30:31], v[30:31], v[32:33] op_sel_hi:[1,0]
	v_pk_mul_f32 v[34:35], v[26:27], v[32:33] op_sel_hi:[1,0]
	v_pk_mul_f32 v[26:27], v[24:25], v[32:33] op_sel_hi:[1,0]
	v_cvt_pk_bf16_f32 v24, v28, v29
	v_mad_i64_i32 v[28:29], s[36:37], v48, s75, v[120:121]
	v_cvt_pk_bf16_f32 v25, v30, v31
	v_cvt_pk_bf16_f32 v26, v26, v27
	v_cvt_pk_bf16_f32 v27, v34, v35
	v_lshl_add_u64 v[28:29], v[28:29], 0, v[122:123]
	global_store_dwordx4 v[28:29], v[24:27], off
	v_pk_mul_f32 v[22:23], v[22:23], v[32:33] op_sel_hi:[1,0]
	v_pk_mul_f32 v[20:21], v[20:21], v[32:33] op_sel_hi:[1,0]
	v_pk_mul_f32 v[24:25], v[18:19], v[32:33] op_sel_hi:[1,0]
	v_pk_mul_f32 v[18:19], v[16:17], v[32:33] op_sel_hi:[1,0]
	v_add_u32_e32 v32, 0xb0, v142
	v_cvt_pk_bf16_f32 v16, v20, v21
	v_cvt_pk_bf16_f32 v17, v22, v23
	v_cvt_pk_bf16_f32 v18, v18, v19
	v_cvt_pk_bf16_f32 v19, v24, v25
	v_ashrrev_i32_e32 v33, 31, v32
	global_store_dwordx4 v[28:29], v[16:19], off offset:256
	s_nop 1
	v_mov_b32_e32 v16, v253
	v_pk_mul_f32 v[12:13], v[12:13], v[16:17] op_sel_hi:[1,0]
	v_pk_mul_f32 v[14:15], v[14:15], v[16:17] op_sel_hi:[1,0]
	v_pk_mul_f32 v[18:19], v[10:11], v[16:17] op_sel_hi:[1,0]
	v_pk_mul_f32 v[10:11], v[8:9], v[16:17] op_sel_hi:[1,0]
	v_cvt_pk_bf16_f32 v8, v12, v13
	v_mad_i64_i32 v[12:13], s[36:37], v32, s75, v[120:121]
	v_cvt_pk_bf16_f32 v9, v14, v15
	v_cvt_pk_bf16_f32 v10, v10, v11
	v_cvt_pk_bf16_f32 v11, v18, v19
	v_lshl_add_u64 v[12:13], v[12:13], 0, v[122:123]
	global_store_dwordx4 v[12:13], v[8:11], off
	v_pk_mul_f32 v[6:7], v[6:7], v[16:17] op_sel_hi:[1,0]
	v_pk_mul_f32 v[4:5], v[4:5], v[16:17] op_sel_hi:[1,0]
	v_pk_mul_f32 v[8:9], v[2:3], v[16:17] op_sel_hi:[1,0]
	v_pk_mul_f32 v[2:3], v[0:1], v[16:17] op_sel_hi:[1,0]
	v_cvt_pk_bf16_f32 v0, v4, v5
	v_cvt_pk_bf16_f32 v1, v6, v7
	v_cvt_pk_bf16_f32 v2, v2, v3
	v_cvt_pk_bf16_f32 v3, v8, v9
	s_mov_b64 s[36:37], -1
	s_and_b64 vcc, exec, s[2:3]
	global_store_dwordx4 v[12:13], v[0:3], off offset:256
	s_cbranch_vccnz .LBB0_1235
	s_andn2_b64 vcc, exec, s[12:13]
	s_cbranch_vccnz .LBB0_1234
	s_barrier
	s_branch .LBB0_1234
